# v6 + NSA tile loop edge: next-tile descriptor read before the barrier; K/V LDS bases formed pre-barrier; all 15 fragment ds_reads issued first after the barrier
# speedup vs baseline: 1.0082x; 1.0082x over previous
; #define LAS __attribute__((address_space(3)))
; DI f32x16 mma32(bf16x8 a, bf16x8 b, f32x16 c) { return __builtin_amdgcn_mfma_f32_32x32x16_bf16(a, b, c, 0, 0, 0); }
; DI int crow(int i, int hf) { return (i & 3) + 8 * (i >> 2) + 4 * hf; }
; DI void nsa_item(KA a, LAS unsigned char* lds, const int it) {
;     ...
;         of[0] = ot[0] * g0; of[1] = ot[1] * g0;
;     ...
;     float m_ref = 0.f, l_run = 0.f; f32x16 ot[2] = {ZERO16, ZERO16}; int curtype = 0;
;     for (int i = 0; i < n; ++i) {
;         const int desc = LIST[i]; const int ty = desc >> 8, j = desc & 255;
;         const LAS bf16* Kc = (i & 1) ? Kt1 : Kt; const LAS bf16* Vc = (i & 1) ? VT1 : VT;
;         if (ty != curtype) { const float lt = l_run + __shfl_xor(l_run, 32); const float sc = g1 / lt; of[0] += ot[0] * sc; of[1] += ot[1] * sc; ot[0] = ZERO16; ot[1] = ZERO16; m_ref = 0.f; l_run = 0.f; curtype = ty; }
;         const bool rowoff = (ty == 0) && (((mysel >> j) & 1u) == 0u);
;         const int mode = (j == qb) ? 1 : ((ty == 1 && j == qb - 8) ? 2 : 0);
;         const float init = rowoff ? -INFINITY : -m_ref;
;         f32x16 st[2];
; #pragma unroll
;         for (int i2 = 0; i2 < 16; ++i2) { st[0][i2] = init; st[1][i2] = init; }
; #pragma unroll
;         for (int kt = 0; kt < 2; ++kt)
; #pragma unroll
;             for (int s = 0; s < 4; ++s) { const bf16x8 af = *(const LAS bf16x8*)(Kc + (32 * kt + r) * PA + 16 * s + 8 * hf); st[kt] = mma32(af, bq[s], st[kt]); }
;         if (mode != 0) {
; #pragma unroll
;             for (int kt = 0; kt < 2; ++kt)
; #pragma unroll
;                 for (int i2 = 0; i2 < 16; ++i2) { const int kl = 32 * kt + crow(i2, hf); const bool bad = rowoff || (mode == 1 && kl > tql) || (mode == 2 && kl <= tql); st[kt][i2] = bad ? -INFINITY : st[kt][i2]; }
.LBB0_794:
	v_add_f32_e32 v33, 1.0, v33
	v_rcp_f32_e32 v34, v33
	s_andn2_b64 vcc, exec, s[0:1]
	v_readlane_b32 s90, v254, 47
	v_pk_mul_f32 v[124:125], v[34:35], v[30:31] op_sel_hi:[0,1]
	v_pk_mul_f32 v[120:121], v[34:35], v[28:29] op_sel_hi:[0,1]
	v_pk_mul_f32 v[116:117], v[34:35], v[26:27] op_sel_hi:[0,1]
	v_pk_mul_f32 v[112:113], v[34:35], v[24:25] op_sel_hi:[0,1]
	v_pk_mul_f32 v[108:109], v[34:35], v[22:23] op_sel_hi:[0,1]
	v_pk_mul_f32 v[104:105], v[34:35], v[20:21] op_sel_hi:[0,1]
	v_pk_mul_f32 v[100:101], v[34:35], v[18:19] op_sel_hi:[0,1]
	v_pk_mul_f32 v[96:97], v[34:35], v[16:17] op_sel_hi:[0,1]
	v_pk_mul_f32 v[122:123], v[34:35], v[14:15] op_sel_hi:[0,1]
	v_pk_mul_f32 v[118:119], v[34:35], v[12:13] op_sel_hi:[0,1]
	v_pk_mul_f32 v[114:115], v[34:35], v[10:11] op_sel_hi:[0,1]
	v_pk_mul_f32 v[110:111], v[34:35], v[8:9] op_sel_hi:[0,1]
	v_pk_mul_f32 v[106:107], v[34:35], v[6:7] op_sel_hi:[0,1]
	v_pk_mul_f32 v[102:103], v[34:35], v[4:5] op_sel_hi:[0,1]
	v_pk_mul_f32 v[98:99], v[34:35], v[2:3] op_sel_hi:[0,1]
	v_pk_mul_f32 v[94:95], v[34:35], v[0:1] op_sel_hi:[0,1]
	v_mov_b32_e32 v31, 0
	s_cbranch_vccnz .LBB0_811
	v_cmp_gt_u32_e64 s[0:1], v92, v135
	v_or_b32_e32 v0, 2, v92
	s_sub_i32 s85, 23, s40
	v_writelane_b32 v254, s0, 49
	s_mov_b32 s87, 0
	s_mov_b32 s88, 0
	v_writelane_b32 v254, s1, 50
	v_cmp_le_u32_e64 s[0:1], v92, v135
	v_mov_b32_e32 v137, 0
	v_mov_b32_e32 v16, 0
	v_writelane_b32 v254, s0, 51
	s_nop 1
	v_writelane_b32 v254, s1, 52
	v_cmp_ge_u32_e64 s[0:1], v92, v135
	s_nop 1
	v_writelane_b32 v254, s0, 53
	s_nop 1
	v_writelane_b32 v254, s1, 54
	v_cmp_lt_u32_e64 s[0:1], v92, v135
	s_nop 1
	v_writelane_b32 v254, s0, 55
	s_nop 1
	v_writelane_b32 v254, s1, 56
	v_cmp_gt_u32_e64 s[0:1], v0, v135
	s_nop 1
	v_writelane_b32 v254, s0, 57
	s_nop 1
	v_writelane_b32 v254, s1, 58
	v_cmp_le_u32_e64 s[0:1], v0, v135
	v_or_b32_e32 v0, 3, v92
	s_nop 0
	v_writelane_b32 v254, s0, 59
	s_nop 1
	v_writelane_b32 v254, s1, 60
	v_cmp_gt_u32_e64 s[0:1], v0, v135
	s_nop 1
	v_writelane_b32 v254, s0, 61
	s_nop 1
	v_writelane_b32 v254, s1, 62
	v_cmp_le_u32_e64 s[0:1], v0, v135
	v_or_b32_e32 v0, 8, v92
	s_nop 0
	v_writelane_b32 v254, s0, 63
	s_nop 0
	v_readlane_b32 s86, v254, 13
	v_writelane_b32 v245, s1, 0
	v_cmp_gt_u32_e64 s[0:1], v0, v135
	s_nop 1
	v_writelane_b32 v245, s0, 1
	s_nop 1
	v_writelane_b32 v245, s1, 2
	v_cmp_le_u32_e64 s[0:1], v0, v135
	v_or_b32_e32 v0, 9, v92
	s_nop 0
	v_writelane_b32 v245, s0, 3
	s_nop 1
	v_writelane_b32 v245, s1, 4
	v_cmp_gt_u32_e64 s[0:1], v0, v135
	s_nop 1
	v_writelane_b32 v245, s0, 5
	s_nop 1
	v_writelane_b32 v245, s1, 6
	v_cmp_le_u32_e64 s[0:1], v0, v135
	v_or_b32_e32 v0, 10, v92
	s_nop 0
	v_writelane_b32 v245, s0, 7
	s_nop 1
	v_writelane_b32 v245, s1, 8
	v_cmp_gt_u32_e64 s[0:1], v0, v135
	s_nop 1
	v_writelane_b32 v245, s0, 9
	s_nop 1
	v_writelane_b32 v245, s1, 10
	v_cmp_le_u32_e64 s[0:1], v0, v135
	v_or_b32_e32 v0, 11, v92
	s_nop 0
	v_writelane_b32 v245, s0, 11
	s_nop 1
	v_writelane_b32 v245, s1, 12
	v_cmp_gt_u32_e64 s[0:1], v0, v135
	s_nop 1
	v_writelane_b32 v245, s0, 13
	s_nop 1
	v_writelane_b32 v245, s1, 14
	v_cmp_le_u32_e64 s[0:1], v0, v135
	v_or_b32_e32 v0, 16, v92
	s_nop 0
	v_writelane_b32 v245, s0, 15
	s_nop 1
	v_writelane_b32 v245, s1, 16
	v_cmp_gt_u32_e64 s[0:1], v0, v135
	s_nop 1
	v_writelane_b32 v245, s0, 17
	s_nop 1
	v_writelane_b32 v245, s1, 18
	v_cmp_le_u32_e64 s[0:1], v0, v135
	v_or_b32_e32 v0, 17, v92
	s_nop 0
	v_writelane_b32 v245, s0, 19
	s_nop 1
	v_writelane_b32 v245, s1, 20
	v_cmp_gt_u32_e64 s[0:1], v0, v135
	s_nop 1
	v_writelane_b32 v245, s0, 21
	s_nop 1
	v_writelane_b32 v245, s1, 22
	v_cmp_le_u32_e64 s[0:1], v0, v135
	v_or_b32_e32 v0, 18, v92
	s_nop 0
	v_writelane_b32 v245, s0, 23
	s_nop 1
	v_writelane_b32 v245, s1, 24
	v_cmp_gt_u32_e64 s[0:1], v0, v135
	s_nop 1
	v_writelane_b32 v245, s0, 25
	s_nop 1
	v_writelane_b32 v245, s1, 26
	v_cmp_le_u32_e64 s[0:1], v0, v135
	v_or_b32_e32 v0, 19, v92
	s_nop 0
	v_writelane_b32 v245, s0, 27
	s_nop 1
	v_writelane_b32 v245, s1, 28
	v_cmp_gt_u32_e64 s[0:1], v0, v135
	s_nop 1
	v_writelane_b32 v245, s0, 29
	s_nop 1
	v_writelane_b32 v245, s1, 30
	v_cmp_le_u32_e64 s[0:1], v0, v135
	v_or_b32_e32 v0, 24, v92
	s_nop 0
	v_writelane_b32 v245, s0, 31
	s_nop 1
	v_writelane_b32 v245, s1, 32
	v_cmp_gt_u32_e64 s[0:1], v0, v135
	s_nop 1
	v_writelane_b32 v245, s0, 33
	s_nop 1
	v_writelane_b32 v245, s1, 34
	v_cmp_le_u32_e64 s[0:1], v0, v135
	v_or_b32_e32 v0, 25, v92
	v_cmp_gt_u32_e64 s[92:93], v0, v135
	v_cmp_le_u32_e64 s[94:95], v0, v135
	v_or_b32_e32 v0, 26, v92
	v_cmp_gt_u32_e64 s[96:97], v0, v135
	v_cmp_le_u32_e64 s[6:7], v0, v135
	v_or_b32_e32 v0, 27, v92
	v_cmp_gt_u32_e64 s[8:9], v0, v135
	v_cmp_le_u32_e64 s[10:11], v0, v135
	v_or_b32_e32 v0, 32, v92
	v_cmp_gt_u32_e64 s[12:13], v0, v135
	v_cmp_le_u32_e64 s[14:15], v0, v135
	v_or_b32_e32 v0, 33, v92
	v_cmp_gt_u32_e64 s[16:17], v0, v135
	v_cmp_le_u32_e64 s[18:19], v0, v135
	v_or_b32_e32 v0, 34, v92
	v_cmp_gt_u32_e64 s[20:21], v0, v135
	v_cmp_le_u32_e64 s[22:23], v0, v135
	v_or_b32_e32 v0, 35, v92
	v_cmp_gt_u32_e64 s[24:25], v0, v135
	v_cmp_le_u32_e64 s[26:27], v0, v135
	v_or_b32_e32 v0, 40, v92
	v_cmp_gt_u32_e64 s[28:29], v0, v135
	v_cmp_le_u32_e64 s[30:31], v0, v135
	v_or_b32_e32 v0, 41, v92
	v_cmp_gt_u32_e64 s[34:35], v0, v135
	v_cmp_le_u32_e64 s[36:37], v0, v135
	v_or_b32_e32 v0, 42, v92
	v_cmp_gt_u32_e64 s[38:39], v0, v135
	v_cmp_le_u32_e64 s[4:5], v0, v135
	v_or_b32_e32 v0, 43, v92
	v_writelane_b32 v245, s0, 35
	v_cmp_gt_u32_e64 s[40:41], v0, v135
	v_cmp_le_u32_e64 s[2:3], v0, v135
	v_or_b32_e32 v0, 48, v92
	v_writelane_b32 v245, s1, 36
	v_cmp_gt_u32_e64 s[0:1], v0, v135
	v_cmp_le_u32_e64 s[42:43], v0, v135
; #define LAS __attribute__((address_space(3)))
; DI f32x16 mma32(bf16x8 a, bf16x8 b, f32x16 c) { return __builtin_amdgcn_mfma_f32_32x32x16_bf16(a, b, c, 0, 0, 0); }
; DI void nsa_item(KA a, LAS unsigned char* lds, const int it) {
;     ...
;     float m_ref = 0.f, l_run = 0.f; f32x16 ot[2] = {ZERO16, ZERO16}; int curtype = 0;
;     for (int i = 0; i < n; ++i) {
;         const int desc = LIST[i]; const int ty = desc >> 8, j = desc & 255;
;         const LAS bf16* Kc = (i & 1) ? Kt1 : Kt; const LAS bf16* Vc = (i & 1) ? VT1 : VT;
;         if (ty != curtype) { const float lt = l_run + __shfl_xor(l_run, 32); const float sc = g1 / lt; of[0] += ot[0] * sc; of[1] += ot[1] * sc; ot[0] = ZERO16; ot[1] = ZERO16; m_ref = 0.f; l_run = 0.f; curtype = ty; }
;     ...
;         for (int kt = 0; kt < 2; ++kt)
; #pragma unroll
;             for (int s = 0; s < 4; ++s) { const bf16x8 af = *(const LAS bf16x8*)(Kc + (32 * kt + r) * PA + 16 * s + 8 * hf); st[kt] = mma32(af, bq[s], st[kt]); }
	v_or_b32_e32 v0, 49, v92
	v_cmp_gt_u32_e64 s[44:45], v0, v135
	v_cmp_le_u32_e64 s[46:47], v0, v135
	v_or_b32_e32 v0, 50, v92
	v_cmp_gt_u32_e64 s[48:49], v0, v135
	v_cmp_le_u32_e64 s[50:51], v0, v135
	v_or_b32_e32 v0, 51, v92
	v_cmp_gt_u32_e64 s[52:53], v0, v135
	v_cmp_le_u32_e64 s[54:55], v0, v135
	v_or_b32_e32 v0, 56, v92
	v_cmp_gt_u32_e64 s[56:57], v0, v135
	v_cmp_le_u32_e64 s[58:59], v0, v135
	v_or_b32_e32 v0, 57, v92
	v_cmp_gt_u32_e64 s[60:61], v0, v135
	v_cmp_le_u32_e64 s[62:63], v0, v135
	v_or_b32_e32 v0, 58, v92
	v_cmp_gt_u32_e64 s[64:65], v0, v135
	v_cmp_le_u32_e64 s[66:67], v0, v135
	v_or_b32_e32 v0, 59, v92
	v_cmp_gt_u32_e64 s[68:69], v0, v135
	v_cmp_le_u32_e64 s[70:71], v0, v135
	v_mov_b32_e32 v135, 0
	v_mov_b32_e32 v0, 0
	v_mov_b32_e32 v1, v135
	v_mov_b32_e32 v2, v135
	v_mov_b32_e32 v3, v135
	v_mov_b32_e32 v4, v135
	v_mov_b32_e32 v5, v135
	v_mov_b32_e32 v6, v135
	v_mov_b32_e32 v7, v135
	v_mov_b32_e32 v8, v135
	v_mov_b32_e32 v9, v135
	v_mov_b32_e32 v10, v135
	v_mov_b32_e32 v11, v135
	v_mov_b32_e32 v12, v135
	v_mov_b32_e32 v13, v135
	v_mov_b32_e32 v14, v135
	v_mov_b32_e32 v15, v135
	v_mov_b32_e32 v17, v135
	v_mov_b32_e32 v18, v135
	v_mov_b32_e32 v19, v135
	v_mov_b32_e32 v20, v135
	v_mov_b32_e32 v21, v135
	v_mov_b32_e32 v22, v135
	v_mov_b32_e32 v23, v135
	v_mov_b32_e32 v24, v135
	v_mov_b32_e32 v25, v135
	v_mov_b32_e32 v26, v135
	v_mov_b32_e32 v27, v135
	v_mov_b32_e32 v28, v135
	v_mov_b32_e32 v29, v135
	v_mov_b32_e32 v30, v135
	v_mov_b32_e32 v31, v135
	s_add_i32 s74, s86, -8
	v_mov_b32_e32 v191, s74
	ds_read_b32 v191, v191
	v_add3_u32 v231, 0, v90, v130
	s_movk_i32 s74, 0x4800
	v_add3_u32 v230, s74, v90, v131
	s_waitcnt lgkmcnt(0)
.LBB0_796:
	ds_read_b128 v[144:147], v231
	ds_read_b128 v[148:151], v231 offset:32
	ds_read_b128 v[170:173], v231 offset:64
	ds_read_b128 v[174:177], v231 offset:96
	ds_read_b128 v[178:181], v231 offset:4608
	ds_read_b128 v[182:185], v231 offset:4640
	ds_read_b128 v[186:189], v231 offset:4672
	ds_read_b128 v[206:209], v231 offset:4704
	ds_read_b128 v[210:213], v230
	ds_read_b128 v[218:221], v230 offset:8704
	ds_read_b128 v[222:225], v230 offset:8736
	ds_read_b128 v[214:217], v230 offset:32
	ds_read_b128 v[226:229], v230 offset:64
	ds_read_b128 v[152:155], v230 offset:8768
	ds_read_b128 v[246:249], v230 offset:96
	v_readfirstlane_b32 s78, v191
	s_ashr_i32 s82, s78, 8
	s_cmp_eq_u32 s82, s88
	s_cbranch_scc1 .LBB0_798
	ds_bpermute_b32 v32, v134, v135
	v_mov_b32_e32 v137, 0
	s_mov_b32 s88, s82
	s_waitcnt lgkmcnt(0)
	v_add_f32_e32 v32, v135, v32
	v_div_scale_f32 v33, s[74:75], v32, v32, v93
	v_rcp_f32_e32 v34, v33
	v_div_scale_f32 v35, vcc, v93, v32, v93
	v_mov_b32_e32 v135, 0
	v_fma_f32 v36, -v33, v34, 1.0
	v_fmac_f32_e32 v34, v36, v34
	v_mul_f32_e32 v36, v35, v34
	v_fma_f32 v37, -v33, v36, v35
	v_fmac_f32_e32 v36, v37, v34
	v_fma_f32 v33, -v33, v36, v35
	v_div_fmas_f32 v33, v33, v34, v36
	v_div_fixup_f32 v32, v33, v32, v93
	v_pk_fma_f32 v[124:125], v[30:31], v[32:33], v[124:125] op_sel_hi:[1,0,1]
	v_pk_fma_f32 v[120:121], v[28:29], v[32:33], v[120:121] op_sel_hi:[1,0,1]
	v_pk_fma_f32 v[116:117], v[26:27], v[32:33], v[116:117] op_sel_hi:[1,0,1]
	v_pk_fma_f32 v[112:113], v[24:25], v[32:33], v[112:113] op_sel_hi:[1,0,1]
	v_pk_fma_f32 v[108:109], v[22:23], v[32:33], v[108:109] op_sel_hi:[1,0,1]
	v_pk_fma_f32 v[104:105], v[20:21], v[32:33], v[104:105] op_sel_hi:[1,0,1]
	v_pk_fma_f32 v[100:101], v[18:19], v[32:33], v[100:101] op_sel_hi:[1,0,1]
	v_pk_fma_f32 v[96:97], v[16:17], v[32:33], v[96:97] op_sel_hi:[1,0,1]
	v_pk_fma_f32 v[122:123], v[14:15], v[32:33], v[122:123] op_sel_hi:[1,0,1]
	v_pk_fma_f32 v[118:119], v[12:13], v[32:33], v[118:119] op_sel_hi:[1,0,1]
	v_pk_fma_f32 v[114:115], v[10:11], v[32:33], v[114:115] op_sel_hi:[1,0,1]
	v_pk_fma_f32 v[110:111], v[8:9], v[32:33], v[110:111] op_sel_hi:[1,0,1]
	v_pk_fma_f32 v[106:107], v[6:7], v[32:33], v[106:107] op_sel_hi:[1,0,1]
	v_pk_fma_f32 v[102:103], v[4:5], v[32:33], v[102:103] op_sel_hi:[1,0,1]
	v_pk_fma_f32 v[98:99], v[2:3], v[32:33], v[98:99] op_sel_hi:[1,0,1]
	v_pk_fma_f32 v[94:95], v[0:1], v[32:33], v[94:95] op_sel_hi:[1,0,1]
	v_mov_b32_e32 v0, 0
	v_mov_b32_e32 v1, v137
	v_mov_b32_e32 v2, v137
	v_mov_b32_e32 v3, v137
	v_mov_b32_e32 v4, v137
	v_mov_b32_e32 v5, v137
	v_mov_b32_e32 v6, v137
	v_mov_b32_e32 v7, v137
	v_mov_b32_e32 v8, v137
	v_mov_b32_e32 v9, v137
	v_mov_b32_e32 v10, v137
	v_mov_b32_e32 v11, v137
	v_mov_b32_e32 v12, v137
	v_mov_b32_e32 v13, v137
	v_mov_b32_e32 v14, v137
	v_mov_b32_e32 v15, v137
	v_mov_b32_e32 v16, 0
	v_mov_b32_e32 v17, v137
	v_mov_b32_e32 v18, v137
	v_mov_b32_e32 v19, v137
	v_mov_b32_e32 v20, v137
	v_mov_b32_e32 v21, v137
	v_mov_b32_e32 v22, v137
	v_mov_b32_e32 v23, v137
	v_mov_b32_e32 v24, v137
	v_mov_b32_e32 v25, v137
	v_mov_b32_e32 v26, v137
	v_mov_b32_e32 v27, v137
	v_mov_b32_e32 v28, v137
	v_mov_b32_e32 v29, v137
	v_mov_b32_e32 v30, v137
	v_mov_b32_e32 v31, v137
; #define LAS __attribute__((address_space(3)))
; DI f32x16 mma32(bf16x8 a, bf16x8 b, f32x16 c) { return __builtin_amdgcn_mfma_f32_32x32x16_bf16(a, b, c, 0, 0, 0); }
; DI int crow(int i, int hf) { return (i & 3) + 8 * (i >> 2) + 4 * hf; }
; DI void nsa_item(KA a, LAS unsigned char* lds, const int it) {
;     ...
;         const int desc = LIST[i]; const int ty = desc >> 8, j = desc & 255;
;         const LAS bf16* Kc = (i & 1) ? Kt1 : Kt; const LAS bf16* Vc = (i & 1) ? VT1 : VT;
;         if (ty != curtype) { const float lt = l_run + __shfl_xor(l_run, 32); const float sc = g1 / lt; of[0] += ot[0] * sc; of[1] += ot[1] * sc; ot[0] = ZERO16; ot[1] = ZERO16; m_ref = 0.f; l_run = 0.f; curtype = ty; }
;         const bool rowoff = (ty == 0) && (((mysel >> j) & 1u) == 0u);
;         const int mode = (j == qb) ? 1 : ((ty == 1 && j == qb - 8) ? 2 : 0);
;         const float init = rowoff ? -INFINITY : -m_ref;
;         f32x16 st[2];
; #pragma unroll
;         for (int i2 = 0; i2 < 16; ++i2) { st[0][i2] = init; st[1][i2] = init; }
; #pragma unroll
;         for (int kt = 0; kt < 2; ++kt)
; #pragma unroll
;             for (int s = 0; s < 4; ++s) { const bf16x8 af = *(const LAS bf16x8*)(Kc + (32 * kt + r) * PA + 16 * s + 8 * hf); st[kt] = mma32(af, bq[s], st[kt]); }
;         if (mode != 0) {
; #pragma unroll
;             for (int kt = 0; kt < 2; ++kt)
; #pragma unroll
;                 for (int i2 = 0; i2 < 16; ++i2) { const int kl = 32 * kt + crow(i2, hf); const bool bad = rowoff || (mode == 1 && kl > tql) || (mode == 2 && kl <= tql); st[kt][i2] = bad ? -INFINITY : st[kt][i2]; }
.LBB0_798:
	s_and_b32 s83, s78, 0xff
	s_and_b32 s76, s87, 1
	s_bitcmp1_b32 s87, 0
	s_cselect_b64 s[74:75], -1, 0
	s_cmp_eq_u32 s76, 0
	s_cselect_b64 s[76:77], -1, 0
	s_and_b64 s[80:81], s[76:77], exec
	v_readlane_b32 s79, v254, 14
	s_cselect_b32 s89, 0, s79
	v_add3_u32 v89, s89, v90, v130
	s_cmpk_lt_u32 s78, 0x100
	s_cselect_b64 s[80:81], -1, 0
	s_lshl_b32 s78, 1, s78
	v_and_b32_e32 v32, s78, v141
	v_cmp_eq_u32_e32 vcc, 0, v32
	s_and_b64 s[78:79], s[80:81], vcc
	v_cndmask_b32_e64 v32, -v137, v240, s[78:79]
	v_mov_b32_e32 v33, v32
	v_mov_b32_e32 v34, v32
	v_mov_b32_e32 v35, v32
	v_mov_b32_e32 v36, v32
	v_mov_b32_e32 v37, v32
	v_mov_b32_e32 v38, v32
	v_mov_b32_e32 v39, v32
	v_mov_b32_e32 v40, v32
	v_mov_b32_e32 v41, v32
	v_mov_b32_e32 v42, v32
	v_mov_b32_e32 v43, v32
	v_mov_b32_e32 v44, v32
	v_mov_b32_e32 v45, v32
	v_mov_b32_e32 v46, v32
	v_mov_b32_e32 v47, v32
	s_cmp_eq_u32 s83, s90
	s_cselect_b64 s[80:81], -1, 0
	s_waitcnt lgkmcnt(14)
	v_mfma_f32_32x32x16_bf16 v[48:63], v[144:147], v[72:75], v[32:47]
	s_cmp_eq_u32 s83, s85
	s_cselect_b64 vcc, -1, 0
	s_cmp_eq_u32 s82, 1
	s_cselect_b64 s[82:83], -1, 0
	s_and_b64 s[82:83], s[82:83], vcc
	s_or_b64 vcc, s[80:81], s[82:83]
	s_andn2_b64 vcc, exec, vcc
	s_waitcnt lgkmcnt(13)
	v_mfma_f32_32x32x16_bf16 v[48:63], v[148:151], v[64:67], v[48:63]
	s_waitcnt lgkmcnt(12)
	v_mfma_f32_32x32x16_bf16 v[48:63], v[170:173], v[68:71], v[48:63]
	s_waitcnt lgkmcnt(11)
	v_mfma_f32_32x32x16_bf16 v[48:63], v[174:177], v[76:79], v[48:63]
	s_waitcnt lgkmcnt(10)
	v_mfma_f32_32x32x16_bf16 v[32:47], v[178:181], v[72:75], v[32:47]
	s_waitcnt lgkmcnt(9)
	v_mfma_f32_32x32x16_bf16 v[32:47], v[182:185], v[64:67], v[32:47]
	s_waitcnt lgkmcnt(8)
	v_mfma_f32_32x32x16_bf16 v[32:47], v[186:189], v[68:71], v[32:47]
	s_waitcnt lgkmcnt(7)
	v_mfma_f32_32x32x16_bf16 v[32:47], v[206:209], v[76:79], v[32:47]
	ds_read_b128 v[148:151], v230 offset:8800
	s_cbranch_vccnz .LBB0_800
	s_xor_b64 vcc, s[80:81], -1
	s_and_b64 s[82:83], vcc, s[82:83]
	v_readlane_b32 vcc_lo, v254, 49
	v_readlane_b32 vcc_hi, v254, 50
	s_mov_b32 s89, s91
	v_readlane_b32 s90, v254, 51
	s_and_b64 vcc, s[80:81], vcc
	v_readlane_b32 s91, v254, 52
	s_or_b64 vcc, s[78:79], vcc
	s_and_b64 s[90:91], s[82:83], s[90:91]
	s_or_b64 vcc, vcc, s[90:91]
	v_readlane_b32 s90, v254, 53
	v_cndmask_b32_e32 v48, v48, v240, vcc
	v_readlane_b32 s91, v254, 54
	v_readlane_b32 vcc_lo, v254, 55
	s_and_b64 s[90:91], s[80:81], s[90:91]
	v_readlane_b32 vcc_hi, v254, 56
	s_or_b64 s[90:91], s[78:79], s[90:91]
	s_and_b64 vcc, s[82:83], vcc
	s_or_b64 vcc, s[90:91], vcc
	v_readlane_b32 s90, v254, 57
	v_cndmask_b32_e32 v49, v49, v240, vcc
	v_readlane_b32 s91, v254, 58
	v_readlane_b32 vcc_lo, v254, 59
	s_and_b64 s[90:91], s[80:81], s[90:91]
	v_readlane_b32 vcc_hi, v254, 60
	s_or_b64 s[90:91], s[78:79], s[90:91]
	s_and_b64 vcc, s[82:83], vcc
	s_or_b64 vcc, s[90:91], vcc
	v_readlane_b32 s90, v254, 61
	v_cndmask_b32_e32 v50, v50, v240, vcc
	v_readlane_b32 s91, v254, 62
	v_readlane_b32 vcc_lo, v254, 63
	s_and_b64 s[90:91], s[80:81], s[90:91]
	v_readlane_b32 vcc_hi, v245, 0
	s_or_b64 s[90:91], s[78:79], s[90:91]
	s_and_b64 vcc, s[82:83], vcc
	s_or_b64 vcc, s[90:91], vcc
	v_readlane_b32 s90, v245, 1
	v_cndmask_b32_e32 v51, v51, v240, vcc
	v_readlane_b32 s91, v245, 2
	v_readlane_b32 vcc_lo, v245, 3
	s_and_b64 s[90:91], s[80:81], s[90:91]
	v_readlane_b32 vcc_hi, v245, 4
	s_or_b64 s[90:91], s[78:79], s[90:91]
	s_and_b64 vcc, s[82:83], vcc
	s_or_b64 vcc, s[90:91], vcc
	v_readlane_b32 s90, v245, 5
	v_cndmask_b32_e32 v52, v52, v240, vcc
	v_readlane_b32 s91, v245, 6
	v_readlane_b32 vcc_lo, v245, 7
	s_and_b64 s[90:91], s[80:81], s[90:91]
	v_readlane_b32 vcc_hi, v245, 8
	s_or_b64 s[90:91], s[78:79], s[90:91]
	s_and_b64 vcc, s[82:83], vcc
	s_or_b64 vcc, s[90:91], vcc
	v_readlane_b32 s90, v245, 9
	v_cndmask_b32_e32 v53, v53, v240, vcc
	v_readlane_b32 s91, v245, 10
	v_readlane_b32 vcc_lo, v245, 11
	s_and_b64 s[90:91], s[80:81], s[90:91]
	v_readlane_b32 vcc_hi, v245, 12
	s_or_b64 s[90:91], s[78:79], s[90:91]
	s_and_b64 vcc, s[82:83], vcc
	s_or_b64 vcc, s[90:91], vcc
	v_readlane_b32 s90, v245, 13
	v_cndmask_b32_e32 v54, v54, v240, vcc
	v_readlane_b32 s91, v245, 14
	v_readlane_b32 vcc_lo, v245, 15
	s_and_b64 s[90:91], s[80:81], s[90:91]
	v_readlane_b32 vcc_hi, v245, 16
	s_or_b64 s[90:91], s[78:79], s[90:91]
	s_and_b64 vcc, s[82:83], vcc
	s_or_b64 vcc, s[90:91], vcc
	v_readlane_b32 s90, v245, 17
	v_cndmask_b32_e32 v55, v55, v240, vcc
	v_readlane_b32 s91, v245, 18
	v_readlane_b32 vcc_lo, v245, 19
	s_and_b64 s[90:91], s[80:81], s[90:91]
	v_readlane_b32 vcc_hi, v245, 20
	s_or_b64 s[90:91], s[78:79], s[90:91]
	s_and_b64 vcc, s[82:83], vcc
	s_or_b64 vcc, s[90:91], vcc
	v_readlane_b32 s90, v245, 21
; DI int crow(int i, int hf) { return (i & 3) + 8 * (i >> 2) + 4 * hf; }
; DI void nsa_item(KA a, LAS unsigned char* lds, const int it) {
;     ...
;         if (mode != 0) {
; #pragma unroll
;             for (int kt = 0; kt < 2; ++kt)
; #pragma unroll
;                 for (int i2 = 0; i2 < 16; ++i2) { const int kl = 32 * kt + crow(i2, hf); const bool bad = rowoff || (mode == 1 && kl > tql) || (mode == 2 && kl <= tql); st[kt][i2] = bad ? -INFINITY : st[kt][i2]; }
;         }
	v_cndmask_b32_e32 v56, v56, v240, vcc
	v_readlane_b32 s91, v245, 22
	v_readlane_b32 vcc_lo, v245, 23
	s_and_b64 s[90:91], s[80:81], s[90:91]
	v_readlane_b32 vcc_hi, v245, 24
	s_or_b64 s[90:91], s[78:79], s[90:91]
	s_and_b64 vcc, s[82:83], vcc
	s_or_b64 vcc, s[90:91], vcc
	v_readlane_b32 s90, v245, 25
	v_cndmask_b32_e32 v57, v57, v240, vcc
	v_readlane_b32 s91, v245, 26
	v_readlane_b32 vcc_lo, v245, 27
	s_and_b64 s[90:91], s[80:81], s[90:91]
	v_readlane_b32 vcc_hi, v245, 28
	s_or_b64 s[90:91], s[78:79], s[90:91]
	s_and_b64 vcc, s[82:83], vcc
	s_or_b64 vcc, s[90:91], vcc
	v_readlane_b32 s90, v245, 29
	v_cndmask_b32_e32 v58, v58, v240, vcc
	v_readlane_b32 s91, v245, 30
	v_readlane_b32 vcc_lo, v245, 31
	s_and_b64 s[90:91], s[80:81], s[90:91]
	v_readlane_b32 vcc_hi, v245, 32
	s_or_b64 s[90:91], s[78:79], s[90:91]
	s_and_b64 vcc, s[82:83], vcc
	s_or_b64 vcc, s[90:91], vcc
	v_readlane_b32 s90, v245, 33
	v_cndmask_b32_e32 v59, v59, v240, vcc
	v_readlane_b32 s91, v245, 34
	v_readlane_b32 vcc_lo, v245, 35
	s_and_b64 s[90:91], s[80:81], s[90:91]
	v_readlane_b32 vcc_hi, v245, 36
	s_or_b64 s[90:91], s[78:79], s[90:91]
	s_and_b64 vcc, s[82:83], vcc
	s_or_b64 vcc, s[90:91], vcc
	s_and_b64 s[90:91], s[80:81], s[92:93]
	v_cndmask_b32_e32 v60, v60, v240, vcc
	s_or_b64 s[90:91], s[78:79], s[90:91]
	s_and_b64 vcc, s[82:83], s[94:95]
	s_or_b64 vcc, s[90:91], vcc
	s_and_b64 s[90:91], s[80:81], s[96:97]
	v_cndmask_b32_e32 v61, v61, v240, vcc
	s_or_b64 s[90:91], s[78:79], s[90:91]
	s_and_b64 vcc, s[82:83], s[6:7]
	s_or_b64 vcc, s[90:91], vcc
	s_and_b64 s[90:91], s[80:81], s[8:9]
	v_cndmask_b32_e32 v62, v62, v240, vcc
	s_or_b64 s[90:91], s[78:79], s[90:91]
	s_and_b64 vcc, s[82:83], s[10:11]
	s_or_b64 vcc, s[90:91], vcc
	s_and_b64 s[90:91], s[80:81], s[12:13]
	v_cndmask_b32_e32 v63, v63, v240, vcc
	s_or_b64 s[90:91], s[78:79], s[90:91]
	s_and_b64 vcc, s[82:83], s[14:15]
	s_or_b64 vcc, s[90:91], vcc
	s_and_b64 s[90:91], s[80:81], s[16:17]
	v_cndmask_b32_e32 v32, v32, v240, vcc
	s_or_b64 s[90:91], s[78:79], s[90:91]
	s_and_b64 vcc, s[82:83], s[18:19]
	s_or_b64 vcc, s[90:91], vcc
	s_and_b64 s[90:91], s[80:81], s[20:21]
	v_cndmask_b32_e32 v33, v33, v240, vcc
	s_or_b64 s[90:91], s[78:79], s[90:91]
	s_and_b64 vcc, s[82:83], s[22:23]
	s_or_b64 vcc, s[90:91], vcc
	s_and_b64 s[90:91], s[80:81], s[24:25]
	v_cndmask_b32_e32 v34, v34, v240, vcc
	s_or_b64 s[90:91], s[78:79], s[90:91]
	s_and_b64 vcc, s[82:83], s[26:27]
	s_or_b64 vcc, s[90:91], vcc
	s_and_b64 s[90:91], s[80:81], s[28:29]
	v_cndmask_b32_e32 v35, v35, v240, vcc
	s_or_b64 s[90:91], s[78:79], s[90:91]
	s_and_b64 vcc, s[82:83], s[30:31]
	s_or_b64 vcc, s[90:91], vcc
	s_and_b64 s[90:91], s[80:81], s[34:35]
	v_cndmask_b32_e32 v36, v36, v240, vcc
	s_or_b64 s[90:91], s[78:79], s[90:91]
	s_and_b64 vcc, s[82:83], s[36:37]
	s_or_b64 vcc, s[90:91], vcc
	s_and_b64 s[90:91], s[80:81], s[38:39]
	v_cndmask_b32_e32 v37, v37, v240, vcc
	s_or_b64 s[90:91], s[78:79], s[90:91]
	s_and_b64 vcc, s[82:83], s[4:5]
	s_or_b64 vcc, s[90:91], vcc
	s_and_b64 s[90:91], s[80:81], s[40:41]
	v_cndmask_b32_e32 v38, v38, v240, vcc
	s_or_b64 s[90:91], s[78:79], s[90:91]
	s_and_b64 vcc, s[82:83], s[2:3]
	s_or_b64 vcc, s[90:91], vcc
	s_and_b64 s[90:91], s[80:81], s[0:1]
	v_cndmask_b32_e32 v39, v39, v240, vcc
	s_or_b64 s[90:91], s[78:79], s[90:91]
	s_and_b64 vcc, s[82:83], s[42:43]
	s_or_b64 vcc, s[90:91], vcc
	s_and_b64 s[90:91], s[80:81], s[44:45]
	v_cndmask_b32_e32 v40, v40, v240, vcc
	s_or_b64 s[90:91], s[78:79], s[90:91]
	s_and_b64 vcc, s[82:83], s[46:47]
	s_or_b64 vcc, s[90:91], vcc
	s_and_b64 s[90:91], s[80:81], s[48:49]
	v_cndmask_b32_e32 v41, v41, v240, vcc
	s_or_b64 s[90:91], s[78:79], s[90:91]
	s_and_b64 vcc, s[82:83], s[50:51]
	s_or_b64 vcc, s[90:91], vcc
	s_and_b64 s[90:91], s[80:81], s[52:53]
	v_cndmask_b32_e32 v42, v42, v240, vcc
	s_or_b64 s[90:91], s[78:79], s[90:91]
	s_and_b64 vcc, s[82:83], s[54:55]
	s_or_b64 vcc, s[90:91], vcc
	s_and_b64 s[90:91], s[80:81], s[56:57]
	v_cndmask_b32_e32 v43, v43, v240, vcc
	s_or_b64 s[90:91], s[78:79], s[90:91]
	s_and_b64 vcc, s[82:83], s[58:59]
	s_or_b64 vcc, s[90:91], vcc
	s_and_b64 s[90:91], s[80:81], s[60:61]
	v_cndmask_b32_e32 v44, v44, v240, vcc
	s_or_b64 s[90:91], s[78:79], s[90:91]
	s_and_b64 vcc, s[82:83], s[62:63]
	s_or_b64 vcc, s[90:91], vcc
	s_and_b64 s[90:91], s[80:81], s[64:65]
	v_cndmask_b32_e32 v45, v45, v240, vcc
	s_or_b64 s[90:91], s[78:79], s[90:91]
	s_and_b64 vcc, s[82:83], s[66:67]
	s_and_b64 s[80:81], s[80:81], s[68:69]
	s_or_b64 vcc, s[90:91], vcc
	s_or_b64 s[78:79], s[78:79], s[80:81]
	s_and_b64 s[80:81], s[82:83], s[70:71]
	v_cndmask_b32_e32 v46, v46, v240, vcc
	s_or_b64 vcc, s[78:79], s[80:81]
	v_readlane_b32 s90, v254, 47
	s_mov_b32 s91, s89
	v_cndmask_b32_e32 v47, v47, v240, vcc

; DI f32x16 mma32(bf16x8 a, bf16x8 b, f32x16 c) { return __builtin_amdgcn_mfma_f32_32x32x16_bf16(a, b, c, 0, 0, 0); }
; DI bf16x8 packp(const f32x16& x, const int h8) { v4u p; p.x = pk2(x[h8 + 0], x[h8 + 1]); p.y = pk2(x[h8 + 2], x[h8 + 3]); p.z = pk2(x[h8 + 4], x[h8 + 5]); p.w = pk2(x[h8 + 6], x[h8 + 7]); return __builtin_bit_cast(bf16x8, p); }
; #define NSA_STORE(Kb, Vb) do { *(LAS v4u*)((Kb) + skey * PA + 8 * sch) = kreg; LAS unsigned* d0_ = (LAS unsigned*)((Vb) + (4 * sdg) * PV + vpos(2 * skp)); \
;         d0_[0] = (vr0.x & 0xffffu) | (vr1.x << 16); d0_[PV / 2] = (vr0.x >> 16) | (vr1.x & 0xffff0000u); d0_[PV] = (vr0.y & 0xffffu) | (vr1.y << 16); d0_[3 * PV / 2] = (vr0.y >> 16) | (vr1.y & 0xffff0000u); } while (0)
; DI void nsa_item(KA a, LAS unsigned char* lds, const int it) {
;     ...
;             for (int i2 = 0; i2 < 16; i2 += 2) { const float p0 = __builtin_amdgcn_exp2f(st[kt][i2]), p1 = __builtin_amdgcn_exp2f(st[kt][i2 + 1]); st[kt][i2] = p0; st[kt][i2 + 1] = p1; ls2 += (f32x2){p0, p1}; }
;         l_run += ls2[0] + ls2[1];
; #pragma unroll
;         for (int sp = 0; sp < 4; ++sp) { const bf16x8 pf = packp(st[sp >> 1], 8 * (sp & 1));
; #pragma unroll
;             for (int dh = 0; dh < 2; ++dh) ot[dh] = mma32(vfrag(Vc, 32 * dh + r, sp, hf), pf, ot[dh]); }
;         if (i + 1 < n) { if (i & 1) NSA_STORE(Kt, VT); else NSA_STORE(Kt1, VT1); if (i + 2 < n) NSA_LOAD(LIST[i + 2]); }
;         __syncthreads();
.LBB0_807:
	s_add_i32 s86, s86, 4
	s_add_i32 s74, s86, -8
	v_mov_b32_e32 v191, s74
	ds_read_b32 v191, v191
	s_bitcmp1_b32 s76, 0
	s_cselect_b32 s74, 0x9000, 0
	s_movk_i32 s75, 0x4800
	s_cselect_b32 s75, 0xb400, s75
	v_add3_u32 v231, s74, v90, v130
	v_add3_u32 v230, s75, v90, v131
	v_pk_add_f32 v[48:49], v[48:49], v[50:51]
	v_pk_add_f32 v[52:53], v[52:53], v[54:55]
	v_pk_add_f32 v[56:57], v[56:57], v[58:59]
	v_pk_add_f32 v[60:61], v[60:61], v[62:63]
	v_pk_add_f32 v[32:33], v[32:33], v[34:35]
	v_pk_add_f32 v[36:37], v[36:37], v[38:39]
	v_pk_add_f32 v[40:41], v[40:41], v[42:43]
	v_pk_add_f32 v[44:45], v[44:45], v[46:47]
	v_pk_add_f32 v[48:49], v[48:49], v[52:53]
	v_pk_add_f32 v[56:57], v[56:57], v[60:61]
	v_pk_add_f32 v[32:33], v[32:33], v[36:37]
	v_pk_add_f32 v[40:41], v[40:41], v[44:45]
	s_cmp_lg_u32 s84, s76
	s_waitcnt lgkmcnt(0)
	s_barrier
	v_pk_add_f32 v[48:49], v[48:49], v[56:57]
	v_pk_add_f32 v[32:33], v[32:33], v[40:41]
	s_nop 0
	v_pk_add_f32 v[32:33], v[32:33], v[48:49]
	s_nop 0
	v_add_f32_e32 v32, v32, v33
	v_add_f32_e32 v135, v135, v32
	s_cbranch_scc0 .LBB0_600
	s_mov_b32 s87, s76
	s_branch .LBB0_796
